# attention loop edges: wave-uniform kt/cw/last-tile tests moved from VALU compares + exec bookkeeping to scalar compares on hoisted SGPR copies
# speedup vs baseline: 1.0059x; 1.0059x over previous
; template <int DQK, bool MIXA, bool PIPE>
; DI void attn_item(const Params& P, int layer, char* smem, int b, int h, int qt) {
;     ...
;     for (int i = 0; i < DQK; ++i) { a1 = fmaxf(a1, fabsf(g1[i])); a2 = fmaxf(a2, fabsf(g2[i])); }
;     mfix = (float)DQK * 1.02f * a1 * a2 * sl2;
;     if (MIXA) {
;       const float b15 = P.rel_bias[15 * 8 + h];
;       float bm = 0.f;
;       for (int i = 0; i < 32; ++i) bm = fmaxf(bm, P.rel_bias[i * 8 + h] - b15);
;       mfix += bm * LOG2E;
;     }
;   }
;   if (MIXA) {
;     const int rel = tid - 192;
;     const float b15 = P.rel_bias[15 * 8 + h];
;     biasT[tid] = (P.rel_bias[t5_bucket(rel) * 8 + h] - b15) * LOG2E;
;   }
;   bf16x8 qf[NS];
; #pragma unroll
;   for (int s = 0; s < NS; ++s) qf[s] = *(const bf16x8*)(Qp + tokq * ldq + 16 * s + 8 * H);
;   const int nkt = 2 * qt + 2;
;   unsigned koff[NKI], voff[2];
; #pragma unroll
;   for (int i = 0; i < NKI; ++i) {
;     const int e = (w * NKI + i) * 64 + lane;
;     const int row = e / KCH, slot = e % KCH;
;     const int c = slot ^ (MIXA ? ((row >> 1) & 7) : ((row >> 2) & 3));
;     koff[i] = (unsigned)((row * ldk + c * 8) * 2);
;   }
; #pragma unroll
;   for (int i = 0; i < 2; ++i) {
;     const int e = (w * 2 + i) * 64 + lane;
;     const int row = e >> 3, slot = e & 7;
;     const int c = slot ^ ((row >> 1) & 7);
;     voff[i] = (unsigned)((row * S_ + c * 8) * 2);
;   }
;   unsigned mwn[2] = {0u, 0u};
;   auto issue_loads = [&](int kt) __attribute__((always_inline)) {
;     const char* kbp = (const char*)(Kp + (size_t)(kt * 64) * ldk);
;     const char* vbp = (const char*)(VT + kt * 64);
;     char* sk = smem + (kt & 1) * STG_B;
; #pragma unroll
;     for (int i = 0; i < NKI; ++i)
;       __builtin_amdgcn_global_load_lds((const unsigned*)(kbp + koff[i]), (unsigned*)(sk + (w * NKI + i) * 1024), 16, 0, 0);
; #pragma unroll
;     for (int i = 0; i < 2; ++i)
;       __builtin_amdgcn_global_load_lds((const unsigned*)(vbp + voff[i]), (unsigned*)(sk + KTILE_B + (w * 2 + i) * 1024), 16, 0, 0);
;     if (MIXA) {
;       if (kt <= cw) {
;         const unsigned* mp = mask + mask_base(b, cw) + (2 * kt) * 64 + (qpos & 63);
;         mwn[0] = mp[0]; mwn[1] = mp[64];
;       }
;     }
;   };
;   issue_loads(0);
;   f32x16 o[2];
; #pragma unroll
;   for (int d = 0; d < 2; ++d)
; #pragma unroll
;     for (int i = 0; i < 16; ++i) o[d][i] = 0.f;
;   float l = 0.f;
.LBB0_84:
	s_add_u32 s20, s65, s18
	s_addc_u32 s21, s66, s19
	global_load_dwordx4 v[4:7], v137, s[20:21] offset:32
	global_load_dwordx4 v[8:11], v137, s[20:21] offset:16
	global_load_dwordx4 v[12:15], v137, s[20:21]
	s_add_u32 s20, s67, s18
	s_addc_u32 s21, s68, s19
	global_load_dwordx4 v[16:19], v137, s[20:21]
	global_load_dwordx4 v[20:23], v137, s[20:21] offset:16
	global_load_dwordx4 v[24:27], v137, s[20:21] offset:32
	s_add_u32 s18, s18, 48
	s_addc_u32 s19, s19, 0
	s_cmpk_eq_i32 s18, 0x180
	s_waitcnt vmcnt(3)
	v_max3_f32 v2, v2, |v12|, |v13|
	s_waitcnt vmcnt(2)
	v_max3_f32 v1, v1, |v16|, |v17|
	v_max3_f32 v2, v2, |v14|, |v15|
	v_max3_f32 v1, v1, |v18|, |v19|
	v_max3_f32 v2, v2, |v8|, |v9|
	s_waitcnt vmcnt(1)
	v_max3_f32 v1, v1, |v20|, |v21|
	v_max3_f32 v2, v2, |v10|, |v11|
	v_max3_f32 v1, v1, |v22|, |v23|
	v_max3_f32 v2, v2, |v4|, |v5|
	s_waitcnt vmcnt(0)
	v_max3_f32 v1, v1, |v24|, |v25|
	v_max3_f32 v2, v2, |v6|, |v7|
	v_max3_f32 v1, v1, |v26|, |v27|
	s_cbranch_scc0 .LBB0_84
	v_lshl_or_b32 v3, v35, 3, s87
	v_ashrrev_i32_e32 v18, 6, v0
	v_mul_u32_u24_e32 v136, 0x300000, v3
	v_lshlrev_b32_e32 v3, 7, v34
	v_lshl_add_u32 v12, v18, 5, v3
	v_and_b32_e32 v20, 31, v0
	v_readlane_b32 s0, v252, 57
	v_or_b32_e32 v10, v12, v20
	v_lshlrev_b32_e32 v6, 14, v35
	v_readlane_b32 s1, v252, 58
	v_ashrrev_i32_e32 v11, 31, v10
	v_mov_b32_e32 v7, v137
	v_mul_f32_e32 v2, 0x42c3d70a, v2
	v_lshl_add_u64 v[8:9], s[0:1], 0, v[136:137]
	v_lshl_add_u64 v[112:113], v[10:11], 0, v[6:7]
	v_mul_f32_e32 v1, v1, v2
	v_mov_b64_e32 v[2:3], s[62:63]
	s_movk_i32 s0, 0x600
	v_bfe_u32 v139, v0, 5, 1
	v_mad_u64_u32 v[2:3], s[18:19], v112, s0, v[2:3]
	v_mad_i32_i24 v3, v113, s0, v3
	v_lshlrev_b32_e32 v6, 4, v139
	v_lshl_add_u64 v[2:3], v[2:3], 0, v[6:7]
	v_and_b32_e32 v21, 63, v0
	global_load_dwordx4 v[84:87], v[2:3], off
	global_load_dwordx4 v[80:83], v[2:3], off offset:32
	global_load_dwordx4 v[76:79], v[2:3], off offset:64
	global_load_dwordx4 v[72:75], v[2:3], off offset:96
	global_load_dwordx4 v[68:71], v[2:3], off offset:128
	global_load_dwordx4 v[64:67], v[2:3], off offset:160
	v_mul_lo_u32 v2, v18, s72
	v_or_b32_e32 v3, v2, v21
	s_mov_b32 s0, 0x2aaaaaab
	v_mul_hi_i32 v2, v3, s0
	v_lshrrev_b32_e32 v6, 31, v2
	v_ashrrev_i32_e32 v2, 1, v2
	v_add_u32_e32 v2, v2, v6
	v_mul_lo_u32 v6, v2, 12
	v_sub_u32_e32 v6, v3, v6
	v_lshrrev_b32_e32 v7, 2, v2
	v_bitop3_b32 v6, v7, v6, 3 bitop3:0x6c
	v_mul_lo_u32 v2, v2, s72
	v_lshl_add_u32 v2, v6, 4, v2
	v_add_u32_e32 v6, 64, v3
	v_mul_hi_i32 v7, v6, s0
	v_lshrrev_b32_e32 v10, 31, v7
	v_ashrrev_i32_e32 v7, 1, v7
	v_add_u32_e32 v7, v7, v10
	v_mul_lo_u32 v10, v7, 12
	v_sub_u32_e32 v6, v6, v10
	v_lshrrev_b32_e32 v10, 2, v7
	v_bitop3_b32 v6, v10, v6, 3 bitop3:0x6c
	v_mul_lo_u32 v7, v7, s72
	v_add_u32_e32 v3, 0x80, v3
	v_lshl_add_u32 v6, v6, 4, v7
	v_mul_hi_i32 v7, v3, s0
	v_lshrrev_b32_e32 v10, 31, v7
	v_ashrrev_i32_e32 v7, 1, v7
	v_add_u32_e32 v7, v7, v10
	v_mul_lo_u32 v10, v7, 12
	v_sub_u32_e32 v3, v3, v10
	v_lshrrev_b32_e32 v10, 2, v7
	v_bitop3_b32 v3, v10, v3, 3 bitop3:0x6c
	v_mul_lo_u32 v7, v7, s72
	v_lshl_add_u32 v10, v3, 4, v7
	v_mul_f32_e32 v114, 0x3e16c740, v1
	v_lshl_or_b32 v1, v18, 7, v21
	v_lshlrev_b32_e32 v3, 4, v0
	v_lshlrev_b32_e32 v7, 12, v1
	v_bitop3_b32 v22, v21, s92, v3 bitop3:0x48
	v_or_b32_e32 v1, 64, v1
	v_ashrrev_i32_e32 v127, 6, v12
	v_and_or_b32 v12, v7, s25, v22
	v_lshlrev_b32_e32 v7, 12, v1
	v_bitop3_b32 v1, v1, s92, v3 bitop3:0x48
	s_movk_i32 s0, 0x8000
	v_lshlrev_b32_e32 v19, 24, v35
	v_and_or_b32 v14, v7, s0, v1
	v_readlane_b32 s0, v252, 59
	v_or_b32_e32 v4, s88, v19
	v_mov_b32_e32 v5, v137
	v_readlane_b32 s1, v252, 60
	v_mov_b32_e32 v3, v137
	v_lshl_add_u64 v[16:17], v[8:9], 0, v[2:3]
	v_lshl_add_u64 v[4:5], s[0:1], 0, v[4:5]
	s_movk_i32 s0, 0xc00
	v_mul_lo_u32 v132, v18, s0
	v_add_u32_e32 v1, 0x400, v132
	v_readfirstlane_b32 s18, v132
	s_mov_b32 m0, s18
	v_mov_b32_e32 v7, v137
	v_readfirstlane_b32 s18, v1
	v_add_u32_e32 v1, 0x800, v132
	v_lshlrev_b32_e32 v135, 11, v18
	global_load_lds_dwordx4 v[16:17], off
	v_lshl_add_u64 v[16:17], v[8:9], 0, v[6:7]
	s_mov_b32 m0, s18
	v_mov_b32_e32 v11, v137
	v_readfirstlane_b32 s18, v1
	v_add_u32_e32 v1, 0x3000, v135
	global_load_lds_dwordx4 v[16:17], off
	v_lshl_add_u64 v[8:9], v[8:9], 0, v[10:11]
	s_mov_b32 m0, s18
	v_mov_b32_e32 v13, v137
	v_readfirstlane_b32 s18, v1
	v_add_u32_e32 v1, 0x3400, v135
	global_load_lds_dwordx4 v[8:9], off
	v_lshl_add_u64 v[8:9], v[4:5], 0, v[12:13]
	s_mov_b32 m0, s18
	v_mov_b32_e32 v15, v137
	v_readfirstlane_b32 s18, v1
	global_load_lds_dwordx4 v[8:9], off
	v_lshl_add_u64 v[4:5], v[4:5], 0, v[14:15]
	s_mov_b32 m0, s18
	v_and_b32_e32 v1, 19, v0
	global_load_lds_dwordx4 v[4:5], off
	v_lshlrev_b32_e32 v4, 1, v0
	v_lshrrev_b32_e32 v5, 1, v0
	v_and_b32_e32 v4, 8, v4
	v_and_b32_e32 v8, 4, v5
	v_or3_b32 v1, v4, v1, v8
	v_lshrrev_b32_e32 v4, 2, v1
	v_mul_u32_u24_e32 v141, 0xc0, v1
	v_or_b32_e32 v1, 2, v139
	v_bitop3_b32 v1, v4, v1, 3 bitop3:0x6c
	v_lshlrev_b32_e32 v142, 4, v1
	v_or_b32_e32 v1, 4, v139
	v_bitop3_b32 v1, v4, v1, 3 bitop3:0x6c
	v_lshlrev_b32_e32 v143, 4, v1
	v_or_b32_e32 v1, 6, v139
	v_bitop3_b32 v1, v4, v1, 3 bitop3:0x6c
	v_lshlrev_b32_e32 v144, 4, v1
	v_or_b32_e32 v1, 8, v139
	v_bitop3_b32 v1, v4, v1, 3 bitop3:0x6c
	v_lshlrev_b32_e32 v145, 4, v1
	v_or_b32_e32 v1, 10, v139
	v_bfe_u32 v0, v0, 1, 3
	v_bitop3_b32 v1, v4, v1, 3 bitop3:0x6c
	v_lshlrev_b32_e32 v146, 4, v1
	v_bitop3_b32 v1, v139, v0, 4 bitop3:0x36
	v_lshlrev_b32_e32 v130, 4, v1
	v_bitop3_b32 v1, v139, v5, 7 bitop3:0x78
	v_bitop3_b32 v8, v4, v139, 3 bitop3:0x6c
	v_lshlrev_b32_e32 v134, 4, v1
	v_bitop3_b32 v1, v139, v0, 2 bitop3:0x36
	v_bitop3_b32 v0, v139, v0, 6 bitop3:0x36
	v_lshlrev_b32_e32 v4, 12, v21
	s_waitcnt vmcnt(0)
; template <int DQK, bool MIXA, bool PIPE>
; DI void attn_item(const Params& P, int layer, char* smem, int b, int h, int qt) {
;     ...
;   issue_loads(0);
;   f32x16 o[2];
; #pragma unroll
;   for (int d = 0; d < 2; ++d)
; #pragma unroll
;     for (int i = 0; i < 16; ++i) o[d][i] = 0.f;
;   float l = 0.f;
;   const int pr = (l31 & ~12) | ((l31 & 4) << 1) | ((l31 & 8) >> 1);
;   const int swk = MIXA ? ((pr >> 1) & 7) : ((pr >> 2) & 3), swv = (l31 >> 1) & 7;
;   asm volatile("s_waitcnt vmcnt(0)" ::: "memory");
;   __syncthreads();
;   for (int kt = 0; kt < nkt; ++kt) {
;     unsigned mw[2] = {mwn[0], mwn[1]};
;     if (kt + 1 < nkt) issue_loads(kt + 1);
;     ...
;     asm volatile("s_waitcnt vmcnt(0)" ::: "memory");
;     __syncthreads();
;   }
	v_lshlrev_b32_e32 v133, 4, v1
	v_lshlrev_b32_e32 v131, 4, v0
	v_or_b32_e32 v0, s86, v19
	v_mov_b32_e32 v1, v137
	s_mov_b64 s[18:19], 0x1d000080
	v_lshl_or_b32 v4, v18, 19, v4
	v_lshlrev_b32_e32 v128, 1, v34
	v_lshl_add_u64 v[0:1], v[0:1], 0, s[18:19]
	v_and_or_b32 v4, v4, s25, v22
	v_mov_b32_e32 v5, v137
	v_or_b32_e32 v136, 0x18003000, v136
	v_mov_b32_e32 v126, 0
	v_lshlrev_b32_e32 v129, 7, v20
	v_mov_b32_e32 v115, v114
	v_sub_f32_e32 v228, 0, v114
	v_sub_f32_e32 v229, 0, v114
	v_sub_f32_e32 v230, 0, v114
	v_sub_f32_e32 v231, 0, v114
	v_sub_f32_e32 v232, 0, v114
	v_sub_f32_e32 v233, 0, v114
	v_sub_f32_e32 v234, 0, v114
	v_sub_f32_e32 v235, 0, v114
	v_sub_f32_e32 v236, 0, v114
	v_sub_f32_e32 v237, 0, v114
	v_sub_f32_e32 v238, 0, v114
	v_sub_f32_e32 v239, 0, v114
	v_sub_f32_e32 v240, 0, v114
	v_sub_f32_e32 v241, 0, v114
	v_sub_f32_e32 v242, 0, v114
	v_sub_f32_e32 v243, 0, v114
	v_lshlrev_b32_e32 v140, 4, v8
	v_or_b32_e32 v147, 1, v128
	v_lshl_add_u64 v[116:117], v[0:1], 0, v[4:5]
	v_lshl_add_u64 v[118:119], v[0:1], 0, v[14:15]
	s_mov_b32 s22, 0
	v_lshl_add_u64 v[120:121], v[136:137], 0, v[2:3]
	v_lshl_add_u64 v[122:123], v[136:137], 0, v[6:7]
	v_lshl_add_u64 v[124:125], v[136:137], 0, v[10:11]
	s_mov_b64 s[44:45], 0
	v_mov_b32_e32 v0, 0
	v_mov_b32_e32 v1, v126
	v_mov_b32_e32 v2, v126
	v_mov_b32_e32 v3, v126
	v_mov_b32_e32 v4, v126
	v_mov_b32_e32 v5, v126
	v_mov_b32_e32 v6, v126
	v_mov_b32_e32 v7, v126
	v_mov_b32_e32 v8, v126
	v_mov_b32_e32 v9, v126
	v_mov_b32_e32 v10, v126
	v_mov_b32_e32 v11, v126
	v_mov_b32_e32 v12, v126
	v_mov_b32_e32 v13, v126
	v_mov_b32_e32 v14, v126
	v_mov_b32_e32 v15, v126
	v_mov_b32_e32 v16, v126
	v_mov_b32_e32 v17, v126
	v_mov_b32_e32 v18, v126
	v_mov_b32_e32 v19, v126
	v_mov_b32_e32 v20, v126
	v_mov_b32_e32 v21, v126
	v_mov_b32_e32 v22, v126
	v_mov_b32_e32 v23, v126
	v_mov_b32_e32 v24, v126
	v_mov_b32_e32 v25, v126
	v_mov_b32_e32 v26, v126
	v_mov_b32_e32 v27, v126
	v_mov_b32_e32 v28, v126
	v_mov_b32_e32 v29, v126
	v_mov_b32_e32 v30, v126
	v_mov_b32_e32 v31, v126
	s_waitcnt vmcnt(0) lgkmcnt(0)
	s_barrier
	v_readfirstlane_b32 s32, v132
	v_readfirstlane_b32 s73, v135
	s_mov_b64 s[36:37], s[74:75]
	s_mov_b64 s[38:39], s[74:75]
	v_add_u32_e32 v168, v141, v140
	v_add_u32_e32 v170, v141, v142
	v_add_u32_e32 v172, v141, v143
	v_add_u32_e32 v174, v141, v144
	v_add_u32_e32 v176, v141, v145
	v_add_u32_e32 v244, v141, v146
	v_add_u32_e32 v245, v129, v134
	v_add_u32_e32 v246, v129, v133
	v_add_u32_e32 v247, v129, v130
	v_add_u32_e32 v248, v129, v131
	v_readfirstlane_b32 s78, v127
	v_readfirstlane_b32 s79, v147
	s_branch .LBB0_87
.LBB0_86:
	s_waitcnt vmcnt(0)
	s_add_u32 s38, s38, s94
	s_addc_u32 s39, s39, s95
	s_add_u32 s36, s36, s98
	s_addc_u32 s37, s37, s99
	s_mov_b32 s22, s20
	s_waitcnt vmcnt(0) lgkmcnt(0)
	s_barrier
	s_cmp_eq_u32 s20, s79
	s_cbranch_scc1 .LBB0_89
; template <int DQK, bool MIXA, bool PIPE>
; DI void attn_item(const Params& P, int layer, char* smem, int b, int h, int qt) {
;     ...
;     if (kt + 1 < nkt) issue_loads(kt + 1);
;     const char* Ks = smem + (kt & 1) * STG_B;
;     const char* Vs = Ks + KTILE_B;
;     if (kt <= cw) {
;       const int kc = kt;
;       bf16x8 kf[2][NS];
; #pragma unroll
;       for (int kb = 0; kb < 2; ++kb)
; #pragma unroll
;         for (int s = 0; s < NS; ++s) kf[kb][s] = *(const bf16x8*)(Ks + (32 * kb + pr) * KROWB + (((2 * s + H) ^ swk) << 4));
;       __builtin_amdgcn_sched_barrier(0);
;       f32x16 sacc[2];
; #pragma unroll
;       for (int kb = 0; kb < 2; ++kb)
; #pragma unroll
;         for (int i = 0; i < 16; ++i) sacc[kb][i] = 0.f;
; #pragma unroll
;       for (int s = 0; s < NS; ++s) sacc[0] = __builtin_amdgcn_mfma_f32_32x32x16_bf16(kf[0][s], qf[s], sacc[0], 0, 0, 0);
;       bf16x8 vf[2][2][2];
; #pragma unroll
;       for (int d = 0; d < 2; ++d)
; #pragma unroll
;         for (int kb = 0; kb < 2; ++kb)
; #pragma unroll
;           for (int s2 = 0; s2 < 2; ++s2)
;             vf[d][kb][s2] = *(const bf16x8*)(Vs + (d * 32 + l31) * 128 + (((4 * kb + 2 * s2 + H) ^ swv) << 4));
;     ...
;           sacc[1] = __builtin_amdgcn_mfma_f32_32x32x16_bf16(kf[1][s], qf[s], sacc[1], 0, 0, 0);
;           const int cend = (8 * (s + 1)) / NS;
; #pragma unroll
;           for (int c = 0; c < 8; ++c) if (c >= c0 && c < cend) chunk(0, c);
;           c0 = cend;
;           __builtin_amdgcn_sched_barrier(0);
;         }
;       }
;       bf16x8 pf0[2], pf1[2];
; #pragma unroll
;       for (int s2 = 0; s2 < 2; ++s2) { u32x4 t = {pkw[0][s2][0], pkw[0][s2][1], pkw[0][s2][2], pkw[0][s2][3]}; pf0[s2] = __builtin_bit_cast(bf16x8, t); }
; #pragma unroll
;       for (int j = 0; j < 4; ++j) {
;         const int s2 = j >> 1, d = j & 1;
;         o[d] = __builtin_amdgcn_mfma_f32_32x32x16_bf16(vf[d][0][s2], pf0[s2], o[d], 0, 0, 0);
;         chunk(1, 2 * j); chunk(1, 2 * j + 1);
;         __builtin_amdgcn_sched_barrier(0);
;       }
; #pragma unroll
;       for (int s2 = 0; s2 < 2; ++s2) { u32x4 t = {pkw[1][s2][0], pkw[1][s2][1], pkw[1][s2][2], pkw[1][s2][3]}; pf1[s2] = __builtin_bit_cast(bf16x8, t); }
; #pragma unroll
;       for (int j = 0; j < 4; ++j) {
;         const int s2 = j >> 1, d = j & 1;
;         o[d] = __builtin_amdgcn_mfma_f32_32x32x16_bf16(vf[d][1][s2], pf1[s2], o[d], 0, 0, 0);
;       }
.LBB0_87:
	s_add_i32 s20, s22, 1
	s_movk_i32 s21, 0x5000
	s_add_u32 m0, s21, s32
	s_add_u32 s18, s21, s73
	global_load_lds_dwordx4 v120, s[36:37]
	s_add_u32 m0, m0, 0x400
	s_nop 0
	global_load_lds_dwordx4 v122, s[36:37]
	s_add_u32 m0, m0, 0x400
	s_nop 0
	global_load_lds_dwordx4 v124, s[36:37]
	s_add_u32 m0, s18, 0x3000
	global_load_lds_dwordx4 v116, s[38:39]
	s_add_u32 m0, s18, 0x3400
	s_nop 0
	global_load_lds_dwordx4 v118, s[38:39]
	s_cmp_gt_i32 s22, s78
	s_cbranch_scc1 .Lmla_o86
	ds_read_b128 v[32:35], v168
	ds_read_b128 v[36:39], v168 offset:6144
	ds_read_b128 v[40:43], v170
	ds_read_b128 v[148:151], v170 offset:6144
	ds_read_b128 v[44:47], v172
	ds_read_b128 v[152:155], v172 offset:6144
	ds_read_b128 v[88:91], v174
	ds_read_b128 v[156:159], v174 offset:6144
	ds_read_b128 v[92:95], v176
	ds_read_b128 v[208:211], v176 offset:6144
	ds_read_b128 v[96:99], v244
	ds_read_b128 v[212:215], v244 offset:6144
	s_waitcnt lgkmcnt(0)
	v_mfma_f32_32x32x16_bf16 v[48:63], v[32:35], v[84:87], v[228:243]
	ds_read_b128 v[216:219], v245 offset:12288
	ds_read_b128 v[108:111], v246 offset:12288
	v_mfma_f32_32x32x16_bf16 v[48:63], v[40:43], v[80:83], v[48:63]
	v_mfma_f32_32x32x16_bf16 v[48:63], v[44:47], v[76:79], v[48:63]
	v_mfma_f32_32x32x16_bf16 v[48:63], v[88:91], v[72:75], v[48:63]
	ds_read_b128 v[88:91], v247 offset:12288
	v_mfma_f32_32x32x16_bf16 v[48:63], v[92:95], v[68:71], v[48:63]
	v_mfma_f32_32x32x16_bf16 v[48:63], v[96:99], v[64:67], v[48:63]
	ds_read_b128 v[92:95], v248 offset:12288
	ds_read_b128 v[220:223], v245 offset:16384
	ds_read_b128 v[104:107], v246 offset:16384
	ds_read_b128 v[100:103], v247 offset:16384
	ds_read_b128 v[96:99], v248 offset:16384
	s_nop 6
	s_nop 0
	v_exp_f32_e32 v32, v62
	v_exp_f32_e32 v33, v63
	s_nop 0
	v_add_f32_e32 v224, 0, v32
	v_add_f32_e32 v225, 0, v33
	v_cvt_pk_bf16_f32 v63, v32, v33
	v_mfma_f32_32x32x16_bf16 v[32:47], v[36:39], v[84:87], v[228:243]
	v_mfma_f32_32x32x16_bf16 v[32:47], v[148:151], v[80:83], v[32:47]
	v_exp_f32_e32 v60, v60
	v_exp_f32_e32 v61, v61
	s_nop 0
	v_add_f32_e32 v224, v60, v224
	v_add_f32_e32 v225, v61, v225
	v_cvt_pk_bf16_f32 v62, v60, v61
	v_exp_f32_e32 v58, v58
	v_exp_f32_e32 v59, v59
	v_exp_f32_e32 v56, v56
	v_exp_f32_e32 v57, v57
	v_mfma_f32_32x32x16_bf16 v[32:47], v[152:155], v[76:79], v[32:47]
	v_add_f32_e64 v148, v58, v224
	v_add_f32_e64 v149, v59, v225
	v_cvt_pk_bf16_f32 v61, v58, v59
	v_add_f32_e64 v58, v56, v148
	v_add_f32_e64 v59, v57, v149
	v_cvt_pk_bf16_f32 v60, v56, v57
	v_mfma_f32_32x32x16_bf16 v[32:47], v[156:159], v[72:75], v[32:47]
	v_exp_f32_e32 v54, v54
	v_exp_f32_e32 v55, v55
	s_nop 0
	v_add_f32_e32 v56, v54, v58
	v_add_f32_e32 v57, v55, v59
	v_cvt_pk_bf16_f32 v55, v54, v55
	v_mfma_f32_32x32x16_bf16 v[32:47], v[208:211], v[68:71], v[32:47]
	v_exp_f32_e32 v52, v52
	v_exp_f32_e32 v53, v53
	s_nop 0
	v_add_f32_e32 v56, v52, v56
	v_add_f32_e32 v57, v53, v57
	v_cvt_pk_bf16_f32 v54, v52, v53
	v_exp_f32_e32 v50, v50
	v_exp_f32_e32 v51, v51
	v_exp_f32_e32 v48, v48
	v_exp_f32_e32 v49, v49
	v_mfma_f32_32x32x16_bf16 v[32:47], v[212:215], v[64:67], v[32:47]
	v_add_f32_e64 v56, v50, v56
	v_add_f32_e64 v57, v51, v57
	v_cvt_pk_bf16_f32 v53, v50, v51
	v_cvt_pk_bf16_f32 v52, v48, v49
	v_add_f32_e64 v48, v48, v56
	v_add_f32_e64 v49, v49, v57
	s_waitcnt lgkmcnt(0)
	v_mfma_f32_32x32x16_bf16 v[0:15], v[216:219], v[52:55], v[0:15]
	s_nop 3
	v_exp_f32_e32 v46, v46
	v_exp_f32_e32 v47, v47
	v_exp_f32_e32 v44, v44
	v_exp_f32_e32 v45, v45
	v_add_f32_e32 v48, v48, v46
	v_add_f32_e32 v49, v49, v47
	v_cvt_pk_bf16_f32 v47, v46, v47
	v_add_f32_e32 v48, v44, v48
	v_add_f32_e32 v49, v45, v49
	v_cvt_pk_bf16_f32 v46, v44, v45
	v_mfma_f32_32x32x16_bf16 v[16:31], v[220:223], v[52:55], v[16:31]
	v_exp_f32_e32 v42, v42
	v_exp_f32_e32 v43, v43
	v_exp_f32_e32 v40, v40
	v_exp_f32_e32 v41, v41
	v_add_f32_e32 v48, v42, v48
	v_add_f32_e32 v49, v43, v49
	v_cvt_pk_bf16_f32 v45, v42, v43
	v_add_f32_e32 v42, v40, v48
	v_add_f32_e32 v43, v41, v49
	v_cvt_pk_bf16_f32 v44, v40, v41
	v_mfma_f32_32x32x16_bf16 v[0:15], v[108:111], v[60:63], v[0:15]
	v_exp_f32_e32 v38, v38
	v_exp_f32_e32 v39, v39
	v_exp_f32_e32 v36, v36
	v_exp_f32_e32 v37, v37
	v_add_f32_e32 v40, v38, v42
	v_add_f32_e32 v41, v39, v43
	v_cvt_pk_bf16_f32 v39, v38, v39
	v_add_f32_e32 v40, v36, v40
	v_add_f32_e32 v41, v37, v41
	v_cvt_pk_bf16_f32 v38, v36, v37
	v_mfma_f32_32x32x16_bf16 v[16:31], v[104:107], v[60:63], v[16:31]
	v_exp_f32_e32 v34, v34
	v_exp_f32_e32 v35, v35
	v_exp_f32_e32 v32, v32
	v_exp_f32_e32 v33, v33
	v_cvt_pk_bf16_f32 v37, v34, v35
	v_cvt_pk_bf16_f32 v36, v32, v33
	s_nop 1
	v_mfma_f32_32x32x16_bf16 v[0:15], v[88:91], v[36:39], v[0:15]
	v_add_f32_e64 v34, v34, v40
	v_add_f32_e64 v35, v35, v41
	v_add_f32_e64 v32, v32, v34
	v_add_f32_e64 v33, v33, v35
	v_add_f32_e32 v32, v32, v33
	v_add_f32_e32 v126, v126, v32
	v_mfma_f32_32x32x16_bf16 v[16:31], v[100:103], v[36:39], v[16:31]
	v_mfma_f32_32x32x16_bf16 v[0:15], v[92:95], v[44:47], v[0:15]
	v_mfma_f32_32x32x16_bf16 v[16:31], v[96:99], v[44:47], v[16:31]
	s_branch .Lmla_o86

; template <int DQK, bool MIXA, bool PIPE>
; DI void attn_item(const Params& P, int layer, char* smem, int b, int h, int qt) {
;     ...
;     if (kt + 1 < nkt) issue_loads(kt + 1);
;     const char* Ks = smem + (kt & 1) * STG_B;
;     const char* Vs = Ks + KTILE_B;
;     if (kt <= cw) {
;       const int kc = kt;
;       bf16x8 kf[2][NS];
; #pragma unroll
;       for (int kb = 0; kb < 2; ++kb)
; #pragma unroll
;         for (int s = 0; s < NS; ++s) kf[kb][s] = *(const bf16x8*)(Ks + (32 * kb + pr) * KROWB + (((2 * s + H) ^ swk) << 4));
;       __builtin_amdgcn_sched_barrier(0);
;       f32x16 sacc[2];
; #pragma unroll
;       for (int kb = 0; kb < 2; ++kb)
; #pragma unroll
;         for (int i = 0; i < 16; ++i) sacc[kb][i] = 0.f;
; #pragma unroll
;       for (int s = 0; s < NS; ++s) sacc[0] = __builtin_amdgcn_mfma_f32_32x32x16_bf16(kf[0][s], qf[s], sacc[0], 0, 0, 0);
;       bf16x8 vf[2][2][2];
; #pragma unroll
;       for (int d = 0; d < 2; ++d)
; #pragma unroll
;         for (int kb = 0; kb < 2; ++kb)
; #pragma unroll
;           for (int s2 = 0; s2 < 2; ++s2)
;             vf[d][kb][s2] = *(const bf16x8*)(Vs + (d * 32 + l31) * 128 + (((4 * kb + 2 * s2 + H) ^ swv) << 4));
;     ...
;           sacc[1] = __builtin_amdgcn_mfma_f32_32x32x16_bf16(kf[1][s], qf[s], sacc[1], 0, 0, 0);
;           const int cend = (8 * (s + 1)) / NS;
; #pragma unroll
;           for (int c = 0; c < 8; ++c) if (c >= c0 && c < cend) chunk(0, c);
;           c0 = cend;
;           __builtin_amdgcn_sched_barrier(0);
;         }
;       }
;       bf16x8 pf0[2], pf1[2];
; #pragma unroll
;       for (int s2 = 0; s2 < 2; ++s2) { u32x4 t = {pkw[0][s2][0], pkw[0][s2][1], pkw[0][s2][2], pkw[0][s2][3]}; pf0[s2] = __builtin_bit_cast(bf16x8, t); }
; #pragma unroll
;       for (int j = 0; j < 4; ++j) {
;         const int s2 = j >> 1, d = j & 1;
;         o[d] = __builtin_amdgcn_mfma_f32_32x32x16_bf16(vf[d][0][s2], pf0[s2], o[d], 0, 0, 0);
;         chunk(1, 2 * j); chunk(1, 2 * j + 1);
;         __builtin_amdgcn_sched_barrier(0);
;       }
; #pragma unroll
;       for (int s2 = 0; s2 < 2; ++s2) { u32x4 t = {pkw[1][s2][0], pkw[1][s2][1], pkw[1][s2][2], pkw[1][s2][3]}; pf1[s2] = __builtin_bit_cast(bf16x8, t); }
; #pragma unroll
;       for (int j = 0; j < 4; ++j) {
;         const int s2 = j >> 1, d = j & 1;
;         o[d] = __builtin_amdgcn_mfma_f32_32x32x16_bf16(vf[d][1][s2], pf1[s2], o[d], 0, 0, 0);
;       }
.Lmla_o87:
	s_add_i32 s20, s22, 1
	s_mov_b32 s21, 0
	s_add_u32 m0, s21, s32
	s_add_u32 s18, s21, s73
	global_load_lds_dwordx4 v120, s[36:37]
	s_add_u32 m0, m0, 0x400
	s_nop 0
	global_load_lds_dwordx4 v122, s[36:37]
	s_add_u32 m0, m0, 0x400
	s_nop 0
	global_load_lds_dwordx4 v124, s[36:37]
	s_add_u32 m0, s18, 0x3000
	global_load_lds_dwordx4 v116, s[38:39]
	s_add_u32 m0, s18, 0x3400
	s_nop 0
	global_load_lds_dwordx4 v118, s[38:39]
	s_cmp_gt_i32 s22, s78
	s_cbranch_scc1 .LBB0_86
	ds_read_b128 v[32:35], v168 offset:20480
	ds_read_b128 v[36:39], v168 offset:26624
	ds_read_b128 v[40:43], v170 offset:20480
	ds_read_b128 v[148:151], v170 offset:26624
	ds_read_b128 v[44:47], v172 offset:20480
	ds_read_b128 v[152:155], v172 offset:26624
	ds_read_b128 v[88:91], v174 offset:20480
	ds_read_b128 v[156:159], v174 offset:26624
	ds_read_b128 v[92:95], v176 offset:20480
	ds_read_b128 v[208:211], v176 offset:26624
	ds_read_b128 v[96:99], v244 offset:20480
	ds_read_b128 v[212:215], v244 offset:26624
	s_waitcnt lgkmcnt(0)
	v_mfma_f32_32x32x16_bf16 v[48:63], v[32:35], v[84:87], v[228:243]
	ds_read_b128 v[216:219], v245 offset:32768
	ds_read_b128 v[108:111], v246 offset:32768
	v_mfma_f32_32x32x16_bf16 v[48:63], v[40:43], v[80:83], v[48:63]
	v_mfma_f32_32x32x16_bf16 v[48:63], v[44:47], v[76:79], v[48:63]
	v_mfma_f32_32x32x16_bf16 v[48:63], v[88:91], v[72:75], v[48:63]
	ds_read_b128 v[88:91], v247 offset:32768
	v_mfma_f32_32x32x16_bf16 v[48:63], v[92:95], v[68:71], v[48:63]
	v_mfma_f32_32x32x16_bf16 v[48:63], v[96:99], v[64:67], v[48:63]
	ds_read_b128 v[92:95], v248 offset:32768
	ds_read_b128 v[220:223], v245 offset:36864
	ds_read_b128 v[104:107], v246 offset:36864
	ds_read_b128 v[100:103], v247 offset:36864
	ds_read_b128 v[96:99], v248 offset:36864
	s_nop 6
	s_nop 0
	v_exp_f32_e32 v32, v62
	v_exp_f32_e32 v33, v63
	s_nop 0
	v_add_f32_e32 v224, 0, v32
	v_add_f32_e32 v225, 0, v33
	v_cvt_pk_bf16_f32 v63, v32, v33
	v_mfma_f32_32x32x16_bf16 v[32:47], v[36:39], v[84:87], v[228:243]
	v_mfma_f32_32x32x16_bf16 v[32:47], v[148:151], v[80:83], v[32:47]
	v_exp_f32_e32 v60, v60
	v_exp_f32_e32 v61, v61
	s_nop 0
	v_add_f32_e32 v224, v60, v224
	v_add_f32_e32 v225, v61, v225
	v_cvt_pk_bf16_f32 v62, v60, v61
	v_exp_f32_e32 v58, v58
	v_exp_f32_e32 v59, v59
	v_exp_f32_e32 v56, v56
	v_exp_f32_e32 v57, v57
	v_mfma_f32_32x32x16_bf16 v[32:47], v[152:155], v[76:79], v[32:47]
	v_add_f32_e64 v148, v58, v224
	v_add_f32_e64 v149, v59, v225
	v_cvt_pk_bf16_f32 v61, v58, v59
	v_add_f32_e64 v58, v56, v148
	v_add_f32_e64 v59, v57, v149
	v_cvt_pk_bf16_f32 v60, v56, v57
	v_mfma_f32_32x32x16_bf16 v[32:47], v[156:159], v[72:75], v[32:47]
	v_exp_f32_e32 v54, v54
	v_exp_f32_e32 v55, v55
	s_nop 0
	v_add_f32_e32 v56, v54, v58
	v_add_f32_e32 v57, v55, v59
	v_cvt_pk_bf16_f32 v55, v54, v55
	v_mfma_f32_32x32x16_bf16 v[32:47], v[208:211], v[68:71], v[32:47]
	v_exp_f32_e32 v52, v52
	v_exp_f32_e32 v53, v53
	s_nop 0
	v_add_f32_e32 v56, v52, v56
	v_add_f32_e32 v57, v53, v57
	v_cvt_pk_bf16_f32 v54, v52, v53
	v_exp_f32_e32 v50, v50
	v_exp_f32_e32 v51, v51
	v_exp_f32_e32 v48, v48
	v_exp_f32_e32 v49, v49
	v_mfma_f32_32x32x16_bf16 v[32:47], v[212:215], v[64:67], v[32:47]
	v_add_f32_e64 v56, v50, v56
	v_add_f32_e64 v57, v51, v57
	v_cvt_pk_bf16_f32 v53, v50, v51
	v_cvt_pk_bf16_f32 v52, v48, v49
	v_add_f32_e64 v48, v48, v56
	v_add_f32_e64 v49, v49, v57
	s_waitcnt lgkmcnt(0)
	v_mfma_f32_32x32x16_bf16 v[0:15], v[216:219], v[52:55], v[0:15]
	s_nop 3
	v_exp_f32_e32 v46, v46
	v_exp_f32_e32 v47, v47
	v_exp_f32_e32 v44, v44
	v_exp_f32_e32 v45, v45
	v_add_f32_e32 v48, v48, v46
	v_add_f32_e32 v49, v49, v47
	v_cvt_pk_bf16_f32 v47, v46, v47
	v_add_f32_e32 v48, v44, v48
	v_add_f32_e32 v49, v45, v49
	v_cvt_pk_bf16_f32 v46, v44, v45
	v_mfma_f32_32x32x16_bf16 v[16:31], v[220:223], v[52:55], v[16:31]
	v_exp_f32_e32 v42, v42
	v_exp_f32_e32 v43, v43
	v_exp_f32_e32 v40, v40
	v_exp_f32_e32 v41, v41
	v_add_f32_e32 v48, v42, v48
	v_add_f32_e32 v49, v43, v49
	v_cvt_pk_bf16_f32 v45, v42, v43
	v_add_f32_e32 v42, v40, v48
	v_add_f32_e32 v43, v41, v49
	v_cvt_pk_bf16_f32 v44, v40, v41
	v_mfma_f32_32x32x16_bf16 v[0:15], v[108:111], v[60:63], v[0:15]
	v_exp_f32_e32 v38, v38
	v_exp_f32_e32 v39, v39
	v_exp_f32_e32 v36, v36
	v_exp_f32_e32 v37, v37
	v_add_f32_e32 v40, v38, v42
	v_add_f32_e32 v41, v39, v43
	v_cvt_pk_bf16_f32 v39, v38, v39
	v_add_f32_e32 v40, v36, v40
	v_add_f32_e32 v41, v37, v41
	v_cvt_pk_bf16_f32 v38, v36, v37
	v_mfma_f32_32x32x16_bf16 v[16:31], v[104:107], v[60:63], v[16:31]
	v_exp_f32_e32 v34, v34
	v_exp_f32_e32 v35, v35
	v_exp_f32_e32 v32, v32
	v_exp_f32_e32 v33, v33
	v_cvt_pk_bf16_f32 v37, v34, v35
	v_cvt_pk_bf16_f32 v36, v32, v33
	s_nop 1
	v_mfma_f32_32x32x16_bf16 v[0:15], v[88:91], v[36:39], v[0:15]
	v_add_f32_e64 v34, v34, v40
	v_add_f32_e64 v35, v35, v41
	v_add_f32_e64 v32, v32, v34
	v_add_f32_e64 v33, v33, v35
	v_add_f32_e32 v32, v32, v33
	v_add_f32_e32 v126, v126, v32
	v_mfma_f32_32x32x16_bf16 v[16:31], v[100:103], v[36:39], v[16:31]
	v_mfma_f32_32x32x16_bf16 v[0:15], v[92:95], v[44:47], v[0:15]
	v_mfma_f32_32x32x16_bf16 v[16:31], v[96:99], v[44:47], v[16:31]
	s_branch .LBB0_86
; template <int DQK, bool MIXA, bool PIPE>
; DI void attn_item(const Params& P, int layer, char* smem, int b, int h, int qt) {
;     ...
;       bf16x8 kf[2][NS];
; #pragma unroll
;       for (int kb = 0; kb < 2; ++kb)
; #pragma unroll
;         for (int s = 0; s < NS; ++s) kf[kb][s] = *(const bf16x8*)(Ks + (32 * kb + pr) * KROWB + (((2 * s + H) ^ swk) << 4));
;       __builtin_amdgcn_sched_barrier(0);
;       f32x16 sacc[2];
; #pragma unroll
;       for (int kb = 0; kb < 2; ++kb)
; #pragma unroll
;         for (int i = 0; i < 16; ++i) sacc[kb][i] = 0.f;
; #pragma unroll
;       for (int s = 0; s < NS; ++s) sacc[0] = __builtin_amdgcn_mfma_f32_32x32x16_bf16(kf[0][s], qf[s], sacc[0], 0, 0, 0);
;       bf16x8 vf[2][2][2];
; #pragma unroll
;       for (int d = 0; d < 2; ++d)
; #pragma unroll
;         for (int kb = 0; kb < 2; ++kb)
; #pragma unroll
;           for (int s2 = 0; s2 < 2; ++s2)
;             vf[d][kb][s2] = *(const bf16x8*)(Vs + (d * 32 + l31) * 128 + (((4 * kb + 2 * s2 + H) ^ swv) << 4));
;     ...
;           sacc[1] = __builtin_amdgcn_mfma_f32_32x32x16_bf16(kf[1][s], qf[s], sacc[1], 0, 0, 0);
;           const int cend = (8 * (s + 1)) / NS;
; #pragma unroll
;           for (int c = 0; c < 8; ++c) if (c >= c0 && c < cend) chunk(0, c);
;           c0 = cend;
;           __builtin_amdgcn_sched_barrier(0);
;         }
;       }
;       bf16x8 pf0[2], pf1[2];
; #pragma unroll
;       for (int s2 = 0; s2 < 2; ++s2) { u32x4 t = {pkw[0][s2][0], pkw[0][s2][1], pkw[0][s2][2], pkw[0][s2][3]}; pf0[s2] = __builtin_bit_cast(bf16x8, t); }
; #pragma unroll
;       for (int j = 0; j < 4; ++j) {
;         const int s2 = j >> 1, d = j & 1;
;         o[d] = __builtin_amdgcn_mfma_f32_32x32x16_bf16(vf[d][0][s2], pf0[s2], o[d], 0, 0, 0);
;         chunk(1, 2 * j); chunk(1, 2 * j + 1);
;         __builtin_amdgcn_sched_barrier(0);
;       }
; #pragma unroll
;       for (int s2 = 0; s2 < 2; ++s2) { u32x4 t = {pkw[1][s2][0], pkw[1][s2][1], pkw[1][s2][2], pkw[1][s2][3]}; pf1[s2] = __builtin_bit_cast(bf16x8, t); }
; #pragma unroll
;       for (int j = 0; j < 4; ++j) {
;         const int s2 = j >> 1, d = j & 1;
;         o[d] = __builtin_amdgcn_mfma_f32_32x32x16_bf16(vf[d][1][s2], pf1[s2], o[d], 0, 0, 0);
;       }
.LBB0_89:
	v_mov_b32_e32 v32, s21
	s_or_b64 exec, exec, s[44:45]
	v_cmp_lt_i32_e32 vcc, v128, v127
	s_and_saveexec_b64 s[18:19], vcc
	s_cbranch_execz .LBB0_91
	v_add_u32_e32 v33, v32, v141
	v_add_u32_e32 v38, v33, v140
	v_add_u32_e32 v46, v33, v142
	v_add_u32_e32 v47, v33, v143
	v_add_u32_e32 v48, v33, v144
	v_add_u32_e32 v49, v33, v145
	v_add_u32_e32 v33, v33, v146
	ds_read_b128 v[34:37], v38
	ds_read_b128 v[38:41], v38 offset:6144
	ds_read_b128 v[42:45], v46
	ds_read_b128 v[116:119], v46 offset:6144
	ds_read_b128 v[88:91], v47
	ds_read_b128 v[120:123], v47 offset:6144
	ds_read_b128 v[92:95], v48
	ds_read_b128 v[140:143], v48 offset:6144
	ds_read_b128 v[96:99], v49
	ds_read_b128 v[144:147], v49 offset:6144
	ds_read_b128 v[100:103], v33
	ds_read_b128 v[148:151], v33 offset:6144
	s_waitcnt lgkmcnt(11)
	v_mfma_f32_32x32x16_bf16 v[48:63], v[34:37], v[84:87], v[228:243]
	v_add_u32_e32 v32, v32, v129
	v_add_u32_e32 v33, v32, v134
	v_add_u32_e32 v34, v32, v133
	v_add_u32_e32 v35, v32, v130
	v_add_u32_e32 v32, v32, v131
	ds_read_b128 v[152:155], v33 offset:12288
	ds_read_b128 v[108:111], v34 offset:12288
	s_waitcnt lgkmcnt(11)
	v_mfma_f32_32x32x16_bf16 v[48:63], v[42:45], v[80:83], v[48:63]
	s_waitcnt lgkmcnt(9)
	v_mfma_f32_32x32x16_bf16 v[48:63], v[88:91], v[76:79], v[48:63]
	ds_read_b128 v[88:91], v35 offset:12288
	s_waitcnt lgkmcnt(8)
	v_mfma_f32_32x32x16_bf16 v[48:63], v[92:95], v[72:75], v[48:63]
	s_waitcnt lgkmcnt(6)
	v_mfma_f32_32x32x16_bf16 v[48:63], v[96:99], v[68:71], v[48:63]
	s_waitcnt lgkmcnt(4)
	v_mfma_f32_32x32x16_bf16 v[48:63], v[100:103], v[64:67], v[48:63]
	ds_read_b128 v[92:95], v32 offset:12288
	ds_read_b128 v[128:131], v33 offset:16384
	ds_read_b128 v[104:107], v34 offset:16384
	ds_read_b128 v[100:103], v35 offset:16384
	ds_read_b128 v[96:99], v32 offset:16384
	s_nop 6
	s_nop 0
	v_exp_f32_e32 v32, v62
	v_exp_f32_e32 v33, v63
	s_nop 0
	v_add_f32_e32 v124, 0, v32
	v_add_f32_e32 v125, 0, v33
	v_cvt_pk_bf16_f32 v63, v32, v33
	v_mfma_f32_32x32x16_bf16 v[32:47], v[38:41], v[84:87], v[228:243]
	v_mfma_f32_32x32x16_bf16 v[32:47], v[116:119], v[80:83], v[32:47]
	v_exp_f32_e32 v60, v60
	v_exp_f32_e32 v61, v61
	s_nop 0
	v_add_f32_e32 v84, v60, v124
	v_add_f32_e32 v85, v61, v125
	v_cvt_pk_bf16_f32 v62, v60, v61
	v_exp_f32_e32 v58, v58
	v_exp_f32_e32 v59, v59
	v_exp_f32_e32 v56, v56
	v_exp_f32_e32 v57, v57
	v_mfma_f32_32x32x16_bf16 v[32:47], v[120:123], v[76:79], v[32:47]
	v_add_f32_e64 v80, v58, v84
	v_add_f32_e64 v81, v59, v85
	v_cvt_pk_bf16_f32 v61, v58, v59
	v_add_f32_e64 v58, v56, v80
	v_add_f32_e64 v59, v57, v81
	v_cvt_pk_bf16_f32 v60, v56, v57
	v_mfma_f32_32x32x16_bf16 v[32:47], v[140:143], v[72:75], v[32:47]
	v_exp_f32_e32 v54, v54
	v_exp_f32_e32 v55, v55
	s_nop 0
	v_add_f32_e32 v56, v54, v58
	v_add_f32_e32 v57, v55, v59
	v_cvt_pk_bf16_f32 v55, v54, v55
	v_mfma_f32_32x32x16_bf16 v[32:47], v[144:147], v[68:71], v[32:47]
	v_exp_f32_e32 v52, v52
	v_exp_f32_e32 v53, v53
	s_nop 0
	v_add_f32_e32 v56, v52, v56
	v_add_f32_e32 v57, v53, v57
	v_cvt_pk_bf16_f32 v54, v52, v53
	v_exp_f32_e32 v50, v50
	v_exp_f32_e32 v51, v51
	v_exp_f32_e32 v48, v48
	v_exp_f32_e32 v49, v49
	s_waitcnt lgkmcnt(8)
	v_mfma_f32_32x32x16_bf16 v[32:47], v[148:151], v[64:67], v[32:47]
	v_add_f32_e64 v56, v50, v56
	v_add_f32_e64 v57, v51, v57
	v_cvt_pk_bf16_f32 v53, v50, v51
	v_cvt_pk_bf16_f32 v52, v48, v49
	v_add_f32_e64 v48, v48, v56
	v_add_f32_e64 v49, v49, v57
	s_waitcnt lgkmcnt(7)
	v_mfma_f32_32x32x16_bf16 v[0:15], v[152:155], v[52:55], v[0:15]
	s_nop 3
	v_exp_f32_e32 v46, v46
	v_exp_f32_e32 v47, v47
	v_exp_f32_e32 v44, v44
	v_exp_f32_e32 v45, v45
	v_add_f32_e32 v48, v48, v46
	v_add_f32_e32 v49, v49, v47
	v_cvt_pk_bf16_f32 v47, v46, v47
	v_add_f32_e32 v48, v44, v48
	v_add_f32_e32 v49, v45, v49
	v_cvt_pk_bf16_f32 v46, v44, v45
	s_waitcnt lgkmcnt(3)
	v_mfma_f32_32x32x16_bf16 v[16:31], v[128:131], v[52:55], v[16:31]
	v_exp_f32_e32 v42, v42
	v_exp_f32_e32 v43, v43
	v_exp_f32_e32 v40, v40
	v_exp_f32_e32 v41, v41
	v_add_f32_e32 v48, v42, v48
	v_add_f32_e32 v49, v43, v49
	v_cvt_pk_bf16_f32 v45, v42, v43
	v_add_f32_e32 v42, v40, v48
	v_add_f32_e32 v43, v41, v49
	v_cvt_pk_bf16_f32 v44, v40, v41
	v_mfma_f32_32x32x16_bf16 v[0:15], v[108:111], v[60:63], v[0:15]
	v_exp_f32_e32 v38, v38
	v_exp_f32_e32 v39, v39
	v_exp_f32_e32 v36, v36
	v_exp_f32_e32 v37, v37
	v_add_f32_e32 v40, v38, v42
	v_add_f32_e32 v41, v39, v43
	v_cvt_pk_bf16_f32 v39, v38, v39
	v_add_f32_e32 v40, v36, v40
	v_add_f32_e32 v41, v37, v41
	v_cvt_pk_bf16_f32 v38, v36, v37
	s_waitcnt lgkmcnt(2)
	v_mfma_f32_32x32x16_bf16 v[16:31], v[104:107], v[60:63], v[16:31]
	v_exp_f32_e32 v34, v34
	v_exp_f32_e32 v35, v35
	v_exp_f32_e32 v32, v32
	v_exp_f32_e32 v33, v33
	v_cvt_pk_bf16_f32 v37, v34, v35
	v_cvt_pk_bf16_f32 v36, v32, v33
	s_nop 1
	v_mfma_f32_32x32x16_bf16 v[0:15], v[88:91], v[36:39], v[0:15]
	v_add_f32_e64 v34, v34, v40
	v_add_f32_e64 v35, v35, v41
	v_add_f32_e64 v32, v32, v34
	v_add_f32_e64 v33, v33, v35
	v_add_f32_e32 v32, v32, v33
	v_add_f32_e32 v126, v126, v32
	s_waitcnt lgkmcnt(1)
	v_mfma_f32_32x32x16_bf16 v[16:31], v[100:103], v[36:39], v[16:31]
	v_mfma_f32_32x32x16_bf16 v[0:15], v[92:95], v[44:47], v[0:15]
	s_waitcnt lgkmcnt(0)
	v_mfma_f32_32x32x16_bf16 v[16:31], v[96:99], v[44:47], v[16:31]

; template <int DQK, bool MIXA, bool PIPE>
; DI void attn_item(const Params& P, int layer, char* smem, int b, int h, int qt) {
;     ...
;     if (MIXA) {
;       const float b15 = P.rel_bias[15 * 8 + h];
;       float bm = 0.f;
;       for (int i = 0; i < 32; ++i) bm = fmaxf(bm, P.rel_bias[i * 8 + h] - b15);
;       mfix += bm * LOG2E;
;     }
;   }
;   if (MIXA) {
;     const int rel = tid - 192;
;     const float b15 = P.rel_bias[15 * 8 + h];
;     biasT[tid] = (P.rel_bias[t5_bucket(rel) * 8 + h] - b15) * LOG2E;
;   }
;   bf16x8 qf[NS];
; #pragma unroll
;   for (int s = 0; s < NS; ++s) qf[s] = *(const bf16x8*)(Qp + tokq * ldq + 16 * s + 8 * H);
;   const int nkt = 2 * qt + 2;
;   unsigned koff[NKI], voff[2];
; #pragma unroll
;   for (int i = 0; i < NKI; ++i) {
;     const int e = (w * NKI + i) * 64 + lane;
;     const int row = e / KCH, slot = e % KCH;
;     const int c = slot ^ (MIXA ? ((row >> 1) & 7) : ((row >> 2) & 3));
;     koff[i] = (unsigned)((row * ldk + c * 8) * 2);
;   }
; #pragma unroll
;   for (int i = 0; i < 2; ++i) {
;     const int e = (w * 2 + i) * 64 + lane;
;     const int row = e >> 3, slot = e & 7;
;     const int c = slot ^ ((row >> 1) & 7);
;     voff[i] = (unsigned)((row * S_ + c * 8) * 2);
;   }
;   unsigned mwn[2] = {0u, 0u};
;   auto issue_loads = [&](int kt) __attribute__((always_inline)) {
;     const char* kbp = (const char*)(Kp + (size_t)(kt * 64) * ldk);
;     const char* vbp = (const char*)(VT + kt * 64);
;     char* sk = smem + (kt & 1) * STG_B;
; #pragma unroll
;     for (int i = 0; i < NKI; ++i)
;       __builtin_amdgcn_global_load_lds((const unsigned*)(kbp + koff[i]), (unsigned*)(sk + (w * NKI + i) * 1024), 16, 0, 0);
; #pragma unroll
;     for (int i = 0; i < 2; ++i)
;       __builtin_amdgcn_global_load_lds((const unsigned*)(vbp + voff[i]), (unsigned*)(sk + KTILE_B + (w * 2 + i) * 1024), 16, 0, 0);
;     if (MIXA) {
;       if (kt <= cw) {
;         const unsigned* mp = mask + mask_base(b, cw) + (2 * kt) * 64 + (qpos & 63);
;         mwn[0] = mp[0]; mwn[1] = mp[64];
;       }
;     }
;   };
;   issue_loads(0);
;   f32x16 o[2];
; #pragma unroll
;   for (int d = 0; d < 2; ++d)
; #pragma unroll
;     for (int i = 0; i < 16; ++i) o[d][i] = 0.f;
;   float l = 0.f;
;   const int pr = (l31 & ~12) | ((l31 & 4) << 1) | ((l31 & 8) >> 1);
;   const int swk = MIXA ? ((pr >> 1) & 7) : ((pr >> 2) & 3), swv = (l31 >> 1) & 7;
.LBB0_107:
	s_or_b64 exec, exec, s[18:19]
	v_mad_u64_u32 v[126:127], s[18:19], v0, s33, 0
	v_mul_f32_e32 v0, 0x42828f5c, v12
	v_mad_i32_i24 v127, v1, s33, v127
	v_mul_f32_e32 v0, v11, v0
	v_sub_f32_e32 v1, v47, v13
	v_sub_f32_e32 v11, v48, v13
	v_max3_f32 v1, v1, 0, v11
	v_sub_f32_e32 v11, v44, v13
	v_sub_f32_e32 v12, v45, v13
	v_max3_f32 v1, v1, v11, v12
	v_sub_f32_e32 v11, v42, v13
	v_sub_f32_e32 v12, v43, v13
	v_max3_f32 v1, v1, v11, v12
	v_sub_f32_e32 v11, v38, v13
	v_sub_f32_e32 v12, v39, v13
	v_max3_f32 v1, v1, v11, v12
	v_sub_f32_e32 v11, v40, v13
	v_sub_f32_e32 v12, v41, v13
	v_max3_f32 v1, v1, v11, v12
	v_sub_f32_e32 v11, v36, v13
	v_sub_f32_e32 v12, v37, v13
	v_max3_f32 v1, v1, v11, v12
	v_sub_f32_e32 v11, v32, v13
	v_sub_f32_e32 v12, v33, v13
	v_max3_f32 v1, v1, v11, v12
	v_sub_f32_e32 v11, v31, v13
	v_sub_f32_e32 v12, v13, v13
	v_max3_f32 v1, v1, v11, v12
	v_sub_f32_e32 v11, v28, v13
	v_sub_f32_e32 v12, v29, v13
	v_max3_f32 v1, v1, v11, v12
	v_sub_f32_e32 v11, v26, v13
	v_sub_f32_e32 v12, v27, v13
	v_max3_f32 v1, v1, v11, v12
	v_sub_f32_e32 v11, v24, v13
	v_sub_f32_e32 v12, v25, v13
	v_max3_f32 v1, v1, v11, v12
	v_sub_f32_e32 v11, v22, v13
	v_sub_f32_e32 v12, v23, v13
	v_max3_f32 v1, v1, v11, v12
	v_sub_f32_e32 v11, v20, v13
	v_sub_f32_e32 v12, v21, v13
	v_max3_f32 v1, v1, v11, v12
	v_sub_f32_e32 v11, v18, v13
	v_sub_f32_e32 v12, v19, v13
	v_max3_f32 v1, v1, v11, v12
	v_sub_f32_e32 v11, v16, v13
	v_sub_f32_e32 v12, v17, v13
	v_max3_f32 v1, v1, v11, v12
	v_sub_f32_e32 v11, v14, v13
	v_sub_f32_e32 v12, v15, v13
	v_max3_f32 v1, v1, v11, v12
	v_mul_f32_e32 v128, 0x3fb8aa3b, v1
	v_lshlrev_b32_e32 v1, 1, v10
	v_lshrrev_b32_e32 v11, 1, v10
	v_fmac_f32_e32 v128, 0x3e38aa3b, v0
	v_and_b32_e32 v0, 19, v10
	v_and_b32_e32 v1, 8, v1
	v_and_b32_e32 v12, 4, v11
	v_or3_b32 v0, v1, v0, v12
	v_lshrrev_b32_e32 v1, 1, v0
	v_lshlrev_b32_e32 v155, 7, v0
	v_bitop3_b32 v0, v1, v139, 7 bitop3:0x6c
	v_lshlrev_b32_e32 v157, 4, v0
	v_or_b32_e32 v0, 2, v139
	v_bitop3_b32 v0, v1, v0, 7 bitop3:0x6c
	v_lshlrev_b32_e32 v158, 4, v0
	v_or_b32_e32 v0, 4, v139
	v_bitop3_b32 v0, v1, v0, 7 bitop3:0x6c
	v_lshlrev_b32_e32 v159, 4, v0
	v_or_b32_e32 v0, 6, v139
	v_bfe_u32 v10, v10, 1, 3
	v_bitop3_b32 v0, v1, v0, 7 bitop3:0x6c
	v_lshlrev_b32_e32 v160, 4, v0
	v_bitop3_b32 v0, v139, v10, 4 bitop3:0x36
	v_lshlrev_b32_e32 v151, 4, v0
	v_bitop3_b32 v0, v139, v11, 7 bitop3:0x78
	v_lshlrev_b32_e32 v154, 4, v0
	v_bitop3_b32 v0, v139, v10, 2 bitop3:0x36
	v_lshlrev_b32_e32 v153, 4, v0
	v_bitop3_b32 v0, v139, v10, 6 bitop3:0x36
	v_lshlrev_b32_e32 v152, 4, v0
	v_lshlrev_b32_e32 v0, 5, v139
	v_add_lshl_u32 v1, v50, v51, 2
	v_sub_u32_e32 v0, v0, v1
	v_add_u32_e32 v162, 0xa300, v0
	v_lshlrev_b64 v[0:1], 2, v[6:7]
	v_lshlrev_b32_e32 v6, 12, v49
	v_lshl_add_u64 v[130:131], v[8:9], 2, v[0:1]
	v_add_u32_e32 v0, s86, v46
	v_mov_b32_e32 v1, v137
	s_mov_b64 s[18:19], 0x1b000080
	v_lshl_or_b32 v6, v30, 19, v6
	v_lshl_add_u64 v[0:1], v[0:1], 0, s[18:19]
	v_and_or_b32 v6, v6, s25, v54
	v_mov_b32_e32 v7, v137
	v_lshl_add_u64 v[132:133], v[0:1], 0, v[6:7]
	v_add_u32_e32 v6, v52, v49
	v_mov_b32_e32 v7, 0x40000
	v_lshl_add_u32 v6, v6, 12, v7
	s_movk_i32 s0, 0x8000
	v_and_or_b32 v6, v6, s0, v53
	v_readlane_b32 s0, v253, 17
	s_waitcnt vmcnt(0)
	v_mov_b32_e32 v7, v137
	v_readlane_b32 s1, v253, 18
	v_mov_b32_e32 v125, 0
	v_lshl_add_u64 v[134:135], v[0:1], 0, v[6:7]
	v_lshl_add_u64 v[0:1], s[0:1], 0, v[136:137]
	v_lshlrev_b32_e32 v147, 3, v139
	v_lshlrev_b32_e32 v150, 7, v51
	v_add_u32_e32 v148, -2, v145
	v_mov_b32_e32 v129, v128
	v_sub_f32_e32 v228, 0, v128
	v_sub_f32_e32 v229, 0, v128
	v_sub_f32_e32 v230, 0, v128
	v_sub_f32_e32 v231, 0, v128
	v_sub_f32_e32 v232, 0, v128
	v_sub_f32_e32 v233, 0, v128
	v_sub_f32_e32 v234, 0, v128
	v_sub_f32_e32 v235, 0, v128
	v_sub_f32_e32 v236, 0, v128
	v_sub_f32_e32 v237, 0, v128
	v_sub_f32_e32 v238, 0, v128
	v_sub_f32_e32 v239, 0, v128
	v_sub_f32_e32 v240, 0, v128
	v_sub_f32_e32 v241, 0, v128
	v_sub_f32_e32 v242, 0, v128
	v_sub_f32_e32 v243, 0, v128
	v_lshl_or_b32 v149, v34, 1, 1
	v_lshl_add_u64 v[140:141], v[0:1], 0, v[2:3]
	v_lshl_add_u64 v[142:143], v[0:1], 0, v[4:5]
	s_mov_b32 s22, 0
	s_mov_b64 s[58:59], 0
	v_mov_b32_e32 v0, 0
	v_mov_b32_e32 v1, v125
	v_mov_b32_e32 v2, v125
	v_mov_b32_e32 v3, v125
	v_mov_b32_e32 v4, v125
	v_mov_b32_e32 v5, v125
	v_mov_b32_e32 v6, v125
	v_mov_b32_e32 v7, v125
	v_mov_b32_e32 v8, v125
	v_mov_b32_e32 v9, v125
	v_mov_b32_e32 v10, v125
	v_mov_b32_e32 v11, v125
	v_mov_b32_e32 v12, v125
	v_mov_b32_e32 v13, v125
	v_mov_b32_e32 v14, v125
	v_mov_b32_e32 v15, v125
	v_mov_b32_e32 v16, v125
	v_mov_b32_e32 v17, v125
	v_mov_b32_e32 v18, v125
	v_mov_b32_e32 v19, v125
	v_mov_b32_e32 v20, v125
	v_mov_b32_e32 v21, v125
	v_mov_b32_e32 v22, v125
	v_mov_b32_e32 v23, v125
	v_mov_b32_e32 v24, v125
	v_mov_b32_e32 v25, v125
	v_mov_b32_e32 v26, v125
	v_mov_b32_e32 v27, v125
	v_mov_b32_e32 v28, v125
	v_mov_b32_e32 v29, v125
	v_mov_b32_e32 v30, v125
	v_mov_b32_e32 v31, v125
	s_waitcnt vmcnt(0)
	v_mov_b32_e32 v136, v164
	v_mov_b32_e32 v156, v166
	s_waitcnt lgkmcnt(0)
	s_barrier
	v_readfirstlane_b32 s32, v146
	s_mov_b64 s[36:37], s[74:75]
	s_mov_b64 s[38:39], s[74:75]
	s_add_u32 s76, s74, 0x7f00000
	s_addc_u32 s77, s75, 0
	v_add_u32_e32 v168, v155, v157
	v_add_u32_e32 v170, v155, v158
	v_add_u32_e32 v172, v155, v159
	v_add_u32_e32 v174, v155, v160
	v_add_u32_e32 v245, v150, v154
	v_add_u32_e32 v246, v150, v153
	v_add_u32_e32 v247, v150, v151
	v_add_u32_e32 v248, v150, v152
	v_readfirstlane_b32 s78, v145
	v_readfirstlane_b32 s79, v149
	v_readfirstlane_b32 s93, v148
	s_branch .LBB0_110

; template <int DQK, bool MIXA, bool PIPE>
; DI void attn_item(const Params& P, int layer, char* smem, int b, int h, int qt) {
;     ...
;   auto issue_loads = [&](int kt) __attribute__((always_inline)) {
;     const char* kbp = (const char*)(Kp + (size_t)(kt * 64) * ldk);
;     const char* vbp = (const char*)(VT + kt * 64);
;     char* sk = smem + (kt & 1) * STG_B;
; #pragma unroll
;     for (int i = 0; i < NKI; ++i)
;       __builtin_amdgcn_global_load_lds((const unsigned*)(kbp + koff[i]), (unsigned*)(sk + (w * NKI + i) * 1024), 16, 0, 0);
; #pragma unroll
;     for (int i = 0; i < 2; ++i)
;       __builtin_amdgcn_global_load_lds((const unsigned*)(vbp + voff[i]), (unsigned*)(sk + KTILE_B + (w * 2 + i) * 1024), 16, 0, 0);
;     if (MIXA) {
;       if (kt <= cw) {
;         const unsigned* mp = mask + mask_base(b, cw) + (2 * kt) * 64 + (qpos & 63);
;         mwn[0] = mp[0]; mwn[1] = mp[64];
;       }
;     }
;   };
;   issue_loads(0);
;   f32x16 o[2];
; #pragma unroll
;   for (int d = 0; d < 2; ++d)
; #pragma unroll
;     for (int i = 0; i < 16; ++i) o[d][i] = 0.f;
;   float l = 0.f;
;   const int pr = (l31 & ~12) | ((l31 & 4) << 1) | ((l31 & 8) >> 1);
;   const int swk = MIXA ? ((pr >> 1) & 7) : ((pr >> 2) & 3), swv = (l31 >> 1) & 7;
;   asm volatile("s_waitcnt vmcnt(0)" ::: "memory");
;   __syncthreads();
;   for (int kt = 0; kt < nkt; ++kt) {
;     unsigned mw[2] = {mwn[0], mwn[1]};
;     if (kt + 1 < nkt) issue_loads(kt + 1);
;     const char* Ks = smem + (kt & 1) * STG_B;
;     const char* Vs = Ks + KTILE_B;
;     if (kt <= cw) {
;       const int kc = kt;
;       bf16x8 kf[2][NS];
; #pragma unroll
;       for (int kb = 0; kb < 2; ++kb)
; #pragma unroll
;         for (int s = 0; s < NS; ++s) kf[kb][s] = *(const bf16x8*)(Ks + (32 * kb + pr) * KROWB + (((2 * s + H) ^ swk) << 4));
;       __builtin_amdgcn_sched_barrier(0);
;       f32x16 sacc[2];
; #pragma unroll
;       for (int kb = 0; kb < 2; ++kb)
; #pragma unroll
;         for (int i = 0; i < 16; ++i) sacc[kb][i] = 0.f;
; #pragma unroll
;       for (int s = 0; s < NS; ++s) sacc[0] = __builtin_amdgcn_mfma_f32_32x32x16_bf16(kf[0][s], qf[s], sacc[0], 0, 0, 0);
;       bf16x8 vf[2][2][2];
; #pragma unroll
;       for (int d = 0; d < 2; ++d)
; #pragma unroll
;         for (int kb = 0; kb < 2; ++kb)
; #pragma unroll
;           for (int s2 = 0; s2 < 2; ++s2)
.LBB0_109:
	s_waitcnt vmcnt(0)
	s_mov_b64 s[0:1], 0x58000
	s_mov_b64 s[56:57], s[42:43]
	v_add_u32_e32 v162, 0x100, v162
	s_add_u32 s76, s76, s30
	s_addc_u32 s77, s77, s31
	s_add_u32 s38, s38, s94
	s_addc_u32 s39, s39, s95
	s_add_u32 s36, s36, s0
	s_addc_u32 s37, s37, s1
	s_mov_b32 s22, s20
	s_waitcnt vmcnt(0)
	v_mov_b32_e32 v166, v156
	v_mov_b32_e32 v164, v136
	s_waitcnt lgkmcnt(0)
	s_barrier
	s_cmp_eq_u32 s20, s79
	s_cbranch_scc1 .LBB0_145
.LBB0_110:
	s_add_i32 s20, s22, 1
	s_movk_i32 s21, 0x5000
	s_add_u32 m0, s21, s32
	global_load_lds_dwordx4 v140, s[36:37]
	s_add_u32 m0, m0, 0x400
	s_nop 0
	global_load_lds_dwordx4 v142, s[36:37]
	s_add_u32 m0, m0, 0x1c00
	s_nop 0
	global_load_lds_dwordx4 v132, s[38:39]
	s_add_u32 m0, m0, 0x400
	s_nop 0
	global_load_lds_dwordx4 v134, s[38:39]
	s_cmp_lt_i32 s22, s78
	s_cselect_b64 s[42:43], exec, 0
	s_cbranch_scc0 .LBB0_112
	global_load_dword v156, v130, s[76:77] offset:512
	global_load_dword v136, v130, s[76:77] offset:768
.LBB0_112:
	s_cmp_gt_i32 s22, s78
	s_cbranch_scc1 .Lmixa_o_o109
	ds_read_b128 v[36:39], v168
	ds_read_b128 v[32:35], v168 offset:4096
	ds_read_b128 v[40:43], v170
	ds_read_b128 v[120:123], v170 offset:4096
	ds_read_b128 v[44:47], v172
	ds_read_b128 v[116:119], v172 offset:4096
	ds_read_b128 v[80:83], v174
	ds_read_b128 v[108:111], v174 offset:4096
	s_waitcnt lgkmcnt(0)
	v_mfma_f32_32x32x16_bf16 v[48:63], v[36:39], v[76:79], v[228:243]
	ds_read_b128 v[112:115], v245 offset:8192
	ds_read_b128 v[100:103], v246 offset:8192
	v_mfma_f32_32x32x16_bf16 v[48:63], v[40:43], v[72:75], v[48:63]
	v_mfma_f32_32x32x16_bf16 v[48:63], v[44:47], v[68:71], v[48:63]
	v_mfma_f32_32x32x16_bf16 v[48:63], v[80:83], v[64:67], v[48:63]
	ds_read_b128 v[80:83], v247 offset:8192
	ds_read_b128 v[84:87], v248 offset:8192
	ds_read_b128 v[104:107], v245 offset:12288
	ds_read_b128 v[96:99], v246 offset:12288
	ds_read_b128 v[92:95], v247 offset:12288
	ds_read_b128 v[88:91], v248 offset:12288
	s_nop 4
	s_cmp_ge_i32 s22, s93
	s_cbranch_scc1 .Lmixa_near_0

; template <int DQK, bool MIXA, bool PIPE>
; DI void attn_item(const Params& P, int layer, char* smem, int b, int h, int qt) {
;     ...
;   auto issue_loads = [&](int kt) __attribute__((always_inline)) {
;     const char* kbp = (const char*)(Kp + (size_t)(kt * 64) * ldk);
;     const char* vbp = (const char*)(VT + kt * 64);
;     char* sk = smem + (kt & 1) * STG_B;
; #pragma unroll
;     for (int i = 0; i < NKI; ++i)
;       __builtin_amdgcn_global_load_lds((const unsigned*)(kbp + koff[i]), (unsigned*)(sk + (w * NKI + i) * 1024), 16, 0, 0);
; #pragma unroll
;     for (int i = 0; i < 2; ++i)
;       __builtin_amdgcn_global_load_lds((const unsigned*)(vbp + voff[i]), (unsigned*)(sk + KTILE_B + (w * 2 + i) * 1024), 16, 0, 0);
;     if (MIXA) {
;       if (kt <= cw) {
;         const unsigned* mp = mask + mask_base(b, cw) + (2 * kt) * 64 + (qpos & 63);
;         mwn[0] = mp[0]; mwn[1] = mp[64];
;       }
;     }
;   };
;   issue_loads(0);
;   f32x16 o[2];
; #pragma unroll
;   for (int d = 0; d < 2; ++d)
; #pragma unroll
;     for (int i = 0; i < 16; ++i) o[d][i] = 0.f;
;   float l = 0.f;
;   const int pr = (l31 & ~12) | ((l31 & 4) << 1) | ((l31 & 8) >> 1);
;   const int swk = MIXA ? ((pr >> 1) & 7) : ((pr >> 2) & 3), swv = (l31 >> 1) & 7;
;   asm volatile("s_waitcnt vmcnt(0)" ::: "memory");
;   __syncthreads();
;   for (int kt = 0; kt < nkt; ++kt) {
;     unsigned mw[2] = {mwn[0], mwn[1]};
;     if (kt + 1 < nkt) issue_loads(kt + 1);
;     const char* Ks = smem + (kt & 1) * STG_B;
;     const char* Vs = Ks + KTILE_B;
;     if (kt <= cw) {
;       const int kc = kt;
;       bf16x8 kf[2][NS];
; #pragma unroll
;       for (int kb = 0; kb < 2; ++kb)
; #pragma unroll
;         for (int s = 0; s < NS; ++s) kf[kb][s] = *(const bf16x8*)(Ks + (32 * kb + pr) * KROWB + (((2 * s + H) ^ swk) << 4));
;       __builtin_amdgcn_sched_barrier(0);
;       f32x16 sacc[2];
; #pragma unroll
;       for (int kb = 0; kb < 2; ++kb)
; #pragma unroll
;         for (int i = 0; i < 16; ++i) sacc[kb][i] = 0.f;
; #pragma unroll
;       for (int s = 0; s < NS; ++s) sacc[0] = __builtin_amdgcn_mfma_f32_32x32x16_bf16(kf[0][s], qf[s], sacc[0], 0, 0, 0);
;       bf16x8 vf[2][2][2];
; #pragma unroll
;       for (int d = 0; d < 2; ++d)
; #pragma unroll
;         for (int kb = 0; kb < 2; ++kb)
; #pragma unroll
;           for (int s2 = 0; s2 < 2; ++s2)
.Lmixa_o_o110:
	s_add_i32 s20, s22, 1
	s_mov_b32 s21, 0
	s_add_u32 m0, s21, s32
	global_load_lds_dwordx4 v140, s[36:37]
	s_add_u32 m0, m0, 0x400
	s_nop 0
	global_load_lds_dwordx4 v142, s[36:37]
	s_add_u32 m0, m0, 0x1c00
	s_nop 0
	global_load_lds_dwordx4 v132, s[38:39]
	s_add_u32 m0, m0, 0x400
	s_nop 0
	global_load_lds_dwordx4 v134, s[38:39]
	s_cmp_lt_i32 s22, s78
	s_cselect_b64 s[42:43], exec, 0
	s_cbranch_scc0 .Lmixa_o_o112
	global_load_dword v156, v130, s[76:77] offset:512
	global_load_dword v136, v130, s[76:77] offset:768
.Lmixa_o_o112:
	s_cmp_gt_i32 s22, s78
	s_cbranch_scc1 .LBB0_109
	ds_read_b128 v[36:39], v168 offset:20480
	ds_read_b128 v[32:35], v168 offset:24576
	ds_read_b128 v[40:43], v170 offset:20480
	ds_read_b128 v[120:123], v170 offset:24576
	ds_read_b128 v[44:47], v172 offset:20480
	ds_read_b128 v[116:119], v172 offset:24576
	ds_read_b128 v[80:83], v174 offset:20480
	ds_read_b128 v[108:111], v174 offset:24576
	s_waitcnt lgkmcnt(0)
	v_mfma_f32_32x32x16_bf16 v[48:63], v[36:39], v[76:79], v[228:243]
	ds_read_b128 v[112:115], v245 offset:28672
	ds_read_b128 v[100:103], v246 offset:28672
	v_mfma_f32_32x32x16_bf16 v[48:63], v[40:43], v[72:75], v[48:63]
	v_mfma_f32_32x32x16_bf16 v[48:63], v[44:47], v[68:71], v[48:63]
	v_mfma_f32_32x32x16_bf16 v[48:63], v[80:83], v[64:67], v[48:63]
	ds_read_b128 v[80:83], v247 offset:28672
	ds_read_b128 v[84:87], v248 offset:28672
	ds_read_b128 v[104:107], v245 offset:32768
	ds_read_b128 v[96:99], v246 offset:32768
	ds_read_b128 v[92:95], v247 offset:32768
	ds_read_b128 v[88:91], v248 offset:32768
	s_nop 4
	s_cmp_ge_i32 s22, s93
	s_cbranch_scc1 .Lmixa_o_near_0

; template <int DQK, bool MIXA, bool PIPE>
; DI void attn_item(const Params& P, int layer, char* smem, int b, int h, int qt) {
;     ...
;     if (kt <= cw) {
;       const int kc = kt;
;       bf16x8 kf[2][NS];
; #pragma unroll
;       for (int kb = 0; kb < 2; ++kb)
; #pragma unroll
;         for (int s = 0; s < NS; ++s) kf[kb][s] = *(const bf16x8*)(Ks + (32 * kb + pr) * KROWB + (((2 * s + H) ^ swk) << 4));
;       __builtin_amdgcn_sched_barrier(0);
;       f32x16 sacc[2];
; #pragma unroll
;       for (int kb = 0; kb < 2; ++kb)
; #pragma unroll
;         for (int i = 0; i < 16; ++i) sacc[kb][i] = 0.f;
; #pragma unroll
;       for (int s = 0; s < NS; ++s) sacc[0] = __builtin_amdgcn_mfma_f32_32x32x16_bf16(kf[0][s], qf[s], sacc[0], 0, 0, 0);
;       bf16x8 vf[2][2][2];
; #pragma unroll
;       for (int d = 0; d < 2; ++d)
; #pragma unroll
;         for (int kb = 0; kb < 2; ++kb)
; #pragma unroll
;           for (int s2 = 0; s2 < 2; ++s2)
;             vf[d][kb][s2] = *(const bf16x8*)(Vs + (d * 32 + l31) * 128 + (((4 * kb + 2 * s2 + H) ^ swv) << 4));
;       __builtin_amdgcn_sched_barrier(0);
;       const bool near = MIXA && (kc >= cw - 2);
;       f32x2 ls2 = {0.f, 0.f};
;       const f32x2 sl2v = {sl2, sl2}, mfixv = {mfix, mfix};
;       unsigned pkw[2][2][4];
;       unsigned mrot[2];
; #pragma unroll
;       for (int kb = 0; kb < 2; ++kb) mrot[kb] = MIXA ? ((mw[kb] >> (8 * H)) << 8) : 0u;
;       auto chunk = [&](int kb, int c) __attribute__((always_inline)) {
;         const int s2 = 1 - (c >> 2), e = 3 - (c & 3);
;         const int r0 = 8 * s2 + 2 * e;
;         if (MIXA && c == 4) mrot[kb] <<= 8;
;         f32x2 xv2 = {sacc[kb][r0], sacc[kb][r0 + 1]};
;         xv2 = xv2 * sl2v - mfixv;
;         if (MIXA) {
;           if (near) {
;             const int kl = 16 * (r0 >> 3) + 8 * H + (r0 & 7);
;             const int rel = kc * 64 + 32 * kb + kl - qpos;
;             xv2.x += biasT[rel + 192];
;             xv2.y += biasT[rel + 193];
.LBB0_145:
	v_mov_b32_e32 v36, s21
	s_or_b64 exec, exec, s[58:59]
	s_and_saveexec_b64 s[44:45], s[56:57]
	s_cbranch_execz .LBB0_74
	v_add_u32_e32 v32, v36, v155
	v_add_u32_e32 v33, v32, v157
	v_add_u32_e32 v37, v32, v158
	v_add_u32_e32 v46, v32, v159
	v_add_u32_e32 v47, v32, v160
	ds_read_b128 v[38:41], v33
	ds_read_b128 v[32:35], v33 offset:4096
	ds_read_b128 v[42:45], v37
	ds_read_b128 v[120:123], v37 offset:4096
	ds_read_b128 v[80:83], v46
	ds_read_b128 v[116:119], v46 offset:4096
	ds_read_b128 v[84:87], v47
	ds_read_b128 v[108:111], v47 offset:4096
	s_waitcnt lgkmcnt(7)
	v_mfma_f32_32x32x16_bf16 v[48:63], v[38:41], v[76:79], v[228:243]
	v_add_u32_e32 v36, v36, v150
	v_add_u32_e32 v37, v36, v154
	v_add_u32_e32 v38, v36, v153
	v_add_u32_e32 v39, v36, v151
	v_add_u32_e32 v36, v36, v152
	ds_read_b128 v[112:115], v37 offset:8192
	ds_read_b128 v[100:103], v38 offset:8192
	s_waitcnt lgkmcnt(7)
	v_mfma_f32_32x32x16_bf16 v[48:63], v[42:45], v[72:75], v[48:63]
	s_waitcnt lgkmcnt(5)
	v_mfma_f32_32x32x16_bf16 v[48:63], v[80:83], v[68:71], v[48:63]
	ds_read_b128 v[80:83], v39 offset:8192
	s_waitcnt lgkmcnt(4)
	v_mfma_f32_32x32x16_bf16 v[48:63], v[84:87], v[64:67], v[48:63]
	ds_read_b128 v[84:87], v36 offset:8192
	ds_read_b128 v[104:107], v37 offset:12288
	ds_read_b128 v[96:99], v38 offset:12288
	ds_read_b128 v[92:95], v39 offset:12288
	ds_read_b128 v[88:91], v36 offset:12288
	v_add3_u32 v38, v144, v147, 64
	v_cmp_ge_i32_e64 s[42:43], v149, v148
	s_nop 4
	v_sub_u32_e32 v124, v38, v124
	s_and_saveexec_b64 s[18:19], s[42:43]
	s_cbranch_execz .LBB0_148
	v_lshl_add_u32 v38, v124, 2, v181
	ds_read2_b32 v[38:39], v38 offset1:1
	s_waitcnt lgkmcnt(0)
	v_pk_add_f32 v[62:63], v[62:63], v[38:39]

; DI int ltid() { int t = threadIdx.x; asm volatile("" : "+v"(t)); return t; }
; DI void phase_rmsnorm(const float* x, const float* g, bf16* hn) {
;   const int lane = ltid() & 63, w = ltid() >> 6;
;   for (int t = blockIdx.x * 4 + w; t < T_; t += gridDim.x * 4) {
;     const float4* xr = (const float4*)(x + (size_t)t * DM);
;     float4 v[4];
;     float ss = 0.f;
; #pragma unroll
;     for (int i = 0; i < 4; ++i) {
;       v[i] = xr[lane + 64 * i];
;       ss += v[i].x * v[i].x + v[i].y * v[i].y + v[i].z * v[i].z + v[i].w * v[i].w;
;     }
;     ss = wave_sum(ss);
;     const float r = rsqrtf(ss * (1.f / DM) + EPS);
; #pragma unroll
;     for (int i = 0; i < 4; ++i) {
;       const float4 gg = ((const float4*)g)[lane + 64 * i];
.LBB0_178:
	s_movk_i32 s78, 0x7fc
	s_movk_i32 s79, 0xfc04
	s_mov_b32 s93, 0x58000
	s_movk_i32 s73, 0x180
	s_movk_i32 s76, 0x7bf
	s_movk_i32 s77, 0xc1
	v_mov_b32_e32 v1, v161
	v_mov_b32_e32 v0, v161
	v_readlane_b32 s0, v252, 50
	v_ashrrev_i32_e32 v0, 6, v0
	s_nop 0
	v_add_u32_e32 v0, s0, v0
	s_mov_b32 s0, 0x8000
	v_cmp_gt_i32_e32 vcc, s0, v0
	s_and_saveexec_b64 s[0:1], vcc
	v_readlane_b32 s84, v254, 56
	v_readlane_b32 s18, v255, 3
	v_readlane_b32 s85, v254, 57
	v_readlane_b32 s26, v254, 60
	s_mov_b32 s2, 0x800000
	s_movk_i32 s3, 0x7fff
	v_readlane_b32 s19, v255, 4
	s_cbranch_execz .LBB0_181
	v_and_b32_e32 v2, 64, v180
	v_add_u32_e32 v2, 64, v2
	v_xor_b32_e32 v3, 32, v180
	v_cmp_lt_i32_e32 vcc, v3, v2
	v_readlane_b32 s4, v254, 63
	s_lshl_b32 s10, s4, 10
	v_cndmask_b32_e32 v3, v180, v3, vcc
	v_lshlrev_b32_e32 v12, 2, v3
	v_xor_b32_e32 v3, 16, v180
	v_cmp_lt_i32_e32 vcc, v3, v2
	s_ashr_i32 s11, s10, 31
	v_readlane_b32 s40, v252, 16
	v_cndmask_b32_e32 v3, v180, v3, vcc
	v_lshlrev_b32_e32 v13, 2, v3
	v_xor_b32_e32 v3, 8, v180
	v_cmp_lt_i32_e32 vcc, v3, v2
	s_lshl_b64 s[10:11], s[10:11], 2
	v_readlane_b32 s44, v252, 20
	v_cndmask_b32_e32 v3, v180, v3, vcc
	v_lshlrev_b32_e32 v14, 2, v3
	v_xor_b32_e32 v3, 4, v180
	v_cmp_lt_i32_e32 vcc, v3, v2
	v_and_b32_e32 v1, 63, v1
	v_readlane_b32 s45, v252, 21
	v_cndmask_b32_e32 v3, v180, v3, vcc
	v_lshlrev_b32_e32 v15, 2, v3
	v_xor_b32_e32 v3, 2, v180
	v_cmp_lt_i32_e32 vcc, v3, v2
	s_add_u32 s10, s44, s10
	v_lshlrev_b32_e32 v6, 2, v1
	v_cndmask_b32_e32 v3, v180, v3, vcc
	v_lshlrev_b32_e32 v16, 2, v3
	v_xor_b32_e32 v3, 1, v180
	v_cmp_lt_i32_e32 vcc, v3, v2
	s_addc_u32 s11, s45, s11
	v_lshlrev_b32_e32 v136, 4, v1
	v_cndmask_b32_e32 v2, v180, v3, vcc
	v_or_b32_e32 v8, 0x100, v6
	v_or_b32_e32 v10, 0x200, v6
	v_or_b32_e32 v18, 0x300, v6
	v_lshlrev_b32_e32 v17, 2, v2
	v_lshl_add_u64 v[2:3], s[10:11], 0, v[136:137]
	v_lshl_add_u64 v[4:5], s[18:19], 0, v[136:137]
	s_mov_b64 s[10:11], 0
	v_lshlrev_b32_e32 v136, 1, v6
	v_lshlrev_b32_e32 v6, 1, v8
	v_lshlrev_b32_e32 v8, 1, v10
	v_lshlrev_b32_e32 v10, 1, v18
	v_readlane_b32 s41, v252, 17
	v_readlane_b32 s42, v252, 18
	v_readlane_b32 s43, v252, 19
	v_readlane_b32 s46, v252, 22
	v_readlane_b32 s47, v252, 23
	v_readlane_b32 s48, v252, 24
	v_readlane_b32 s49, v252, 25
	v_readlane_b32 s50, v252, 26
	v_readlane_b32 s51, v252, 27
	v_readlane_b32 s52, v252, 28
	v_readlane_b32 s53, v252, 29
	v_readlane_b32 s54, v252, 30
	v_readlane_b32 s55, v252, 31
